# prep: static s_setprio 2 for the wave that owns the tanh/sigmoid columns during the token-mix section
# speedup vs baseline: 1.0145x; 1.0034x over previous
.LBB0_167:
	s_add_i32 s55, s55, s54
	s_cmpk_lt_i32 s55, 0x400
	s_cselect_b64 s[46:47], -1, 0
	s_cmpk_gt_i32 s55, 0x3ff
	v_mov_b32_e32 v111, v152
	s_cselect_b64 s[42:43], -1, 0
	s_nop 0
	v_cmp_gt_i32_e32 vcc, s57, v111
	v_lshlrev_b32_e32 v54, 1, v111
	s_barrier
	s_and_saveexec_b64 s[44:45], vcc
	s_cbranch_execz .LBB0_301
	s_waitcnt vmcnt(21)
	v_and_b32_e32 v57, 0xffff0000, v1
	v_lshlrev_b32_e32 v56, 16, v1
	v_and_b32_e32 v59, 0xffff0000, v0
	v_lshlrev_b32_e32 v58, 16, v0
	v_pk_add_f32 v[58:59], v[58:59], v[56:57] neg_lo:[0,1] neg_hi:[0,1]
	v_cmp_lt_i32_e64 s[6:7], s58, v111
	v_cmp_lt_u32_e64 s[4:5], s59, v111
	v_cmp_lt_u32_e32 vcc, s60, v111
	s_waitcnt vmcnt(5)
	v_pk_fma_f32 v[58:59], v[50:51], v[58:59], v[56:57]
	s_andn2_b64 s[94:95], s[6:7], s[4:5]
	s_or_b64 s[96:97], s[94:95], vcc
	s_nop 1
	v_cndmask_b32_e64 v236, 1.0, 2.0, s[94:95]
	v_cndmask_b32_e64 v238, 0, -1.0, s[94:95]
	v_mov_b32_e32 v237, 0xbfb8aa3b
	v_mul_f32_e32 v237, v236, v237
	s_cmp_eq_u64 s[6:7], 0
	s_cbranch_scc1 .Lpq0_0
	s_setprio 2
	v_pk_mul_f32 v[234:235], v[58:59], v[236:237] op_sel:[0,1] op_sel_hi:[1,1]
	v_exp_f32_e32 v234, v234
	v_exp_f32_e32 v235, v235
	s_nop 0
	v_pk_add_f32 v[234:235], v[234:235], 1.0 op_sel_hi:[1,0]
	v_rcp_f32_e32 v234, v234
	v_rcp_f32_e32 v235, v235
	s_nop 0
	v_pk_fma_f32 v[234:235], v[234:235], v[236:237], v[238:239] op_sel_hi:[1,0,0]
	v_cndmask_b32_e64 v58, v58, v234, s[96:97]
	v_cndmask_b32_e64 v59, v59, v235, s[96:97]

.Lpq0_15:
	s_setprio 0
	s_and_b64 s[4:5], s[46:47], exec
	s_cselect_b32 s4, s55, -1
	s_cmp_lt_i32 s4, 0
	ds_write_b64 v52, v[56:57] offset:54000
	s_cbranch_scc1 .LBB0_301
	s_lshl_b32 s10, s4, 4
	s_and_b32 s4, s4, 0xff
	s_cmp_lg_u32 s4, 0
	v_ashrrev_i32_e32 v55, 31, v54
	s_cbranch_scc0 .LBB0_325
	s_add_i32 s4, s10, -1
	s_mov_b32 s5, s11
	s_lshl_b64 s[4:5], s[4:5], 11
	s_add_u32 s4, s8, s4
	s_addc_u32 s5, s9, s5
	v_lshl_add_u64 v[0:1], v[54:55], 1, s[4:5]
	global_load_dword v0, v[0:1], off
	s_cbranch_execnz .LBB0_300

.LBB0_1049:
	s_add_i32 s55, s55, s54
	s_cmpk_lt_i32 s55, 0x400
	s_cselect_b64 s[46:47], -1, 0
	s_cmpk_gt_i32 s55, 0x3ff
	v_mov_b32_e32 v139, v152
	s_cselect_b64 s[42:43], -1, 0
	s_nop 0
	v_cmp_gt_i32_e32 vcc, s57, v139
	v_lshlrev_b32_e32 v70, 1, v139
	s_barrier
	s_and_saveexec_b64 s[44:45], vcc
	s_cbranch_execz .LBB0_1183
	s_waitcnt vmcnt(22)
	v_and_b32_e32 v73, 0xffff0000, v1
	v_lshlrev_b32_e32 v72, 16, v1
	v_and_b32_e32 v75, 0xffff0000, v0
	v_lshlrev_b32_e32 v74, 16, v0
	v_pk_add_f32 v[74:75], v[74:75], v[72:73] neg_lo:[0,1] neg_hi:[0,1]
	v_cmp_lt_i32_e64 s[6:7], s58, v139
	v_cmp_lt_u32_e64 s[4:5], s59, v139
	v_cmp_lt_u32_e32 vcc, s60, v139
	s_waitcnt vmcnt(6)
	v_pk_fma_f32 v[74:75], v[66:67], v[74:75], v[72:73]
	s_andn2_b64 s[94:95], s[6:7], s[4:5]
	s_or_b64 s[96:97], s[94:95], vcc
	s_nop 1
	v_cndmask_b32_e64 v236, 1.0, 2.0, s[94:95]
	v_cndmask_b32_e64 v238, 0, -1.0, s[94:95]
	v_mov_b32_e32 v237, 0xbfb8aa3b
	v_mul_f32_e32 v237, v236, v237
	s_cmp_eq_u64 s[6:7], 0
	s_cbranch_scc1 .Lpq1_0
	s_setprio 2
	v_pk_mul_f32 v[234:235], v[74:75], v[236:237] op_sel:[0,1] op_sel_hi:[1,1]
	v_exp_f32_e32 v234, v234
	v_exp_f32_e32 v235, v235
	s_nop 0
	v_pk_add_f32 v[234:235], v[234:235], 1.0 op_sel_hi:[1,0]
	v_rcp_f32_e32 v234, v234
	v_rcp_f32_e32 v235, v235
	s_nop 0
	v_pk_fma_f32 v[234:235], v[234:235], v[236:237], v[238:239] op_sel_hi:[1,0,0]
	v_cndmask_b32_e64 v74, v74, v234, s[96:97]
	v_cndmask_b32_e64 v75, v75, v235, s[96:97]

.Lpq1_15:
	s_setprio 0
	s_and_b64 s[4:5], s[46:47], exec
	s_cselect_b32 s4, s55, -1
	s_cmp_lt_i32 s4, 0
	ds_write_b64 v68, v[72:73] offset:54000
	s_cbranch_scc1 .LBB0_1183
	s_lshl_b32 s10, s4, 4
	s_and_b32 s4, s4, 0xff
	s_cmp_lg_u32 s4, 0
	v_ashrrev_i32_e32 v71, 31, v70
	s_cbranch_scc0 .LBB0_1207
	s_add_i32 s4, s10, -1
	s_mov_b32 s5, s11
	s_lshl_b64 s[4:5], s[4:5], 11
	s_add_u32 s4, s8, s4
	s_addc_u32 s5, s9, s5
	v_lshl_add_u64 v[0:1], v[70:71], 1, s[4:5]
	global_load_dword v0, v[0:1], off
	s_cbranch_execnz .LBB0_1182
